# baseline (speedup 1.0000x reference)
; #define tid fresh_tid(wid1)
; template <bool DIFF>
; __device__ __forceinline__ void attn_item(const Params& p, int l, int I, LAS unsigned char* lds, const int tid) {
;     ...
;     const int qrow = qrow0 + 32 * wid + r32;
;     bf16x8 qf[DIFF ? 4 : 6];
;     if (DIFF) {
;         const bf16_t* qp = DQb + (size_t)qrow * 512 + 64 * h + 8 * hi;
;         qf[0] = *(const bf16x8*)(qp); qf[1] = *(const bf16x8*)(qp + 16); qf[2] = *(const bf16x8*)(qp + 32); qf[3] = *(const bf16x8*)(qp + 48);
;     } else {
;         const bf16_t* qp = Qb + (size_t)qrow * 768 + 96 * h + 8 * hi;
; #pragma unroll
;         for (int d0 = 0; d0 < 6; ++d0) qf[d0] = *(const bf16x8*)(qp + 16 * d0);
;     }
;     const int rowk = tid >> 3, c8 = tid & 7;
;     const int rowq = (lane & 15) + 16 * (wid & 3), cq8 = (lane >> 4) + 4 * (wid >> 2);
;     const int rowr = (lane & 15) + 16 * wid, cr4 = lane >> 4;
;     const unsigned kw0 = cq8 * 1024 + rowq * 16, vw = AT_V + (c8 >> 2) * 4096 + rowk * 64 + (c8 & 3) * 16, kw2 = (8 + cr4) * 1024 + rowr * 16;
;     u32x4 g0[2], g1[2], g2[2];
;     auto keyrow = [&](int t) { return t < 4 ? ctxbase + 64 * t : latbase + 64 * (t - 4); };
;     auto gload = [&](int t, const int j) {
;         const int kr0 = keyrow(t);
;         if (DIFF) { g0[j] = *(const u32x4*)(DKb + (size_t)(kr0 + rowq) * 512 + 64 * h + 8 * cq8); g1[j] = *(const u32x4*)(DVb + (size_t)(kr0 + rowk) * 512 + 64 * h + 8 * c8); }
;         else { g0[j] = *(const u32x4*)(KVb + (size_t)(kr0 + rowq) * 1024 + 128 * h + 8 * cq8); g1[j] = *(const u32x4*)(KVb + (size_t)(kr0 + rowk) * 1024 + 128 * h + 64 + 8 * c8);
;             if (tid < 256) g2[j] = *(const u32x4*)(KRb + (size_t)(kr0 + rowr) * 32 + 8 * cr4); }
;     };
;     auto lwrite = [&](int slot, const int j) {
;         LAS unsigned char* sb = lds + slot * AT_SLOT + j * AT_SUB;
;         *(LAS u32x4*)(sb + kw0) = g0[j]; *(LAS u32x4*)(sb + vw) = g1[j];
;         if (!DIFF) { if (tid < 256) *(LAS u32x4*)(sb + kw2) = g2[j]; }
;     };
;     LAS float* scr = (LAS float*)(lds + AT_SCR + wid * 512);
;     float mref1 = 0.f, l1 = 0.f, mref2 = 0.f, l2 = 0.f;
;     f32x16 o1[2], o2[2];
;     float zf = 0.f; asm volatile("" : "+v"(zf));
; #pragma unroll
;     for (int r = 0; r < 16; ++r) { o1[0][r] = zf; o1[1][r] = zf; o2[0][r] = zf; o2[1][r] = zf; }
;     const float sc = (DIFF ? 0.17677669529663687f : 0.10206207261596575f) * LOG2E;
; #pragma unroll
.LBB0_491:
	s_and_b32 s4, s25, 0xffffe000
	s_sub_i32 s30, s4, 64
	s_mov_b32 s4, 0
	s_and_b32 s37, s26, 0xffffff00
	v_mbcnt_lo_u32_b32 v0, -1, s4
	v_mbcnt_hi_u32_b32 v169, -1, v0
	v_add_u32_e32 v4, s24, v169
	s_add_i32 s31, s37, 0x8000
	v_readfirstlane_b32 s4, v4
	s_ashr_i32 s29, s4, 6
	s_lshl_b32 s4, s26, 5
	s_and_b32 s36, s4, 0xffffe000
	s_and_b32 s18, s4, 0xffffff00
	s_mov_b32 s4, 30
	s_mov_b32 s4, 30
	s_mov_b32 s4, 30
	s_mov_b32 s4, 30
	s_ashr_i32 s5, s4, 31
	s_lshl_b64 s[4:5], s[4:5], 3
	s_add_u32 s4, s0, s4
	s_addc_u32 s5, s1, s5
	s_load_dwordx2 s[4:5], s[4:5], 0x0
	s_mov_b32 s8, 30
	v_and_b32_e32 v170, 31, v169
	v_bfe_u32 v171, v169, 5, 1
	v_lshlrev_b32_e32 v192, 4, v171
	s_waitcnt lgkmcnt(0)
	s_add_u32 s6, s4, 0x4000000
	s_mov_b32 s4, 30
	s_addc_u32 s7, s5, 0
	s_ashr_i32 s5, s4, 31
	s_lshl_b64 s[4:5], s[4:5], 3
	s_add_u32 s4, s0, s4
	s_addc_u32 s5, s1, s5
	s_load_dwordx2 s[4:5], s[4:5], 0x0
	s_ashr_i32 s9, s8, 31
	s_lshl_b64 s[8:9], s[8:9], 3
	s_add_u32 s8, s0, s8
	s_addc_u32 s9, s1, s9
	s_lshl_b32 s27, s29, 5
	s_add_i32 s27, s27, s18
	v_or_b32_e32 v0, s27, v170
	v_ashrrev_i32_e32 v1, 31, v0
	s_lshl_b32 s18, s26, 6
	v_lshlrev_b64 v[0:1], 10, v[0:1]
	s_and_b32 s28, s18, 0x1c0
	v_lshl_add_u64 v[0:1], s[6:7], 0, v[0:1]
	s_lshl_b32 s78, s28, 1
	v_lshl_add_u64 v[0:1], v[0:1], 0, s[78:79]
	s_mov_b32 s19, 30
	v_lshl_add_u64 v[2:3], v[0:1], 0, v[192:193]
	s_load_dwordx2 s[8:9], s[8:9], 0x0
	global_load_dwordx4 v[16:19], v[2:3], off
	global_load_dwordx4 v[20:23], v[2:3], off offset:32
	global_load_dwordx4 v[24:27], v[2:3], off offset:64
	global_load_dwordx4 v[28:31], v[2:3], off offset:96
	s_lshl_b32 s18, s29, 4
	s_lshl_b32 s19, s29, 9
	v_ashrrev_i32_e32 v172, 3, v4
	s_waitcnt lgkmcnt(0)
	s_add_u32 s4, s4, 0x11050000
	v_bfe_u32 v5, v169, 4, 2
	v_lshlrev_b32_e32 v6, 10, v169
	v_add_u32_e32 v4, s31, v172
	s_addc_u32 s5, s5, 0
	v_and_b32_e32 v41, 0x1000, v6
	v_and_or_b32 v6, s29, -4, v5
	v_ashrrev_i32_e32 v5, 31, v4
	s_add_u32 s8, s8, 0x13150000
	v_lshlrev_b64 v[32:33], 10, v[4:5]
	s_addc_u32 s9, s9, 0
	v_and_b32_e32 v37, 7, v169
	v_lshl_add_u64 v[32:33], s[8:9], 0, v[32:33]
	v_and_b32_e32 v1, 15, v169
	v_lshl_add_u64 v[32:33], v[32:33], 0, s[78:79]
	v_lshlrev_b32_e32 v38, 4, v37
	v_mov_b32_e32 v39, v193
	v_mov_b32_e32 v0, v193
	v_and_or_b32 v173, s18, 48, v1
	v_lshl_add_u64 v[32:33], v[32:33], 0, v[38:39]
	s_add_i32 s18, s37, 0x8040
	global_load_dwordx4 v[100:103], v[32:33], off
	v_or_b32_e32 v32, s18, v173
	v_ashrrev_i32_e32 v33, 31, v32
	v_lshlrev_b32_e32 v42, 10, v6
	v_lshlrev_b32_e32 v6, 3, v6
	v_lshlrev_b64 v[32:33], 10, v[32:33]
	v_ashrrev_i32_e32 v7, 31, v6
	v_lshl_add_u64 v[32:33], s[4:5], 0, v[32:33]
	v_lshlrev_b64 v[34:35], 1, v[6:7]
	v_or_b32_e32 v4, s31, v173
	v_lshl_add_u64 v[32:33], v[32:33], 0, s[78:79]
	v_ashrrev_i32_e32 v5, 31, v4
	v_lshl_add_u64 v[32:33], v[32:33], 0, v[34:35]
	v_lshlrev_b64 v[4:5], 10, v[4:5]
	global_load_dwordx4 v[108:111], v[32:33], off
	v_add_u32_e32 v32, s18, v172
	v_lshl_add_u64 v[4:5], s[4:5], 0, v[4:5]
	v_ashrrev_i32_e32 v33, 31, v32
	v_lshl_add_u64 v[4:5], v[4:5], 0, s[78:79]
	v_lshlrev_b64 v[32:33], 10, v[32:33]
	v_lshl_add_u64 v[4:5], v[4:5], 0, v[34:35]
	v_lshl_add_u64 v[32:33], s[8:9], 0, v[32:33]
	global_load_dwordx4 v[96:99], v[4:5], off
	v_lshl_add_u64 v[32:33], v[32:33], 0, s[78:79]
	v_lshl_add_u64 v[32:33], v[32:33], 0, v[38:39]
	global_load_dwordx4 v[116:119], v[32:33], off
	s_add_i32 s35, s19, 0
	s_add_i32 s35, s35, 0x14000
	s_add_u32 s4, s4, s78
	v_lshlrev_b32_e32 v40, 4, v169
	s_addc_u32 s5, s5, 0
	v_lshl_or_b32 v174, v173, 4, v42
	v_lshl_add_u64 v[164:165], s[4:5], 0, v[34:35]
	s_add_u32 s4, s8, s78
	v_mov_b32_e32 v14, v0
	v_mov_b32_e32 v15, v0
	s_addc_u32 s5, s9, 0
	v_and_b32_e32 v168, 63, v169
	v_mov_b32_e32 v1, v0
	v_mov_b32_e32 v2, v0
	v_mov_b32_e32 v3, v0
	v_mov_b32_e32 v4, v0
	v_mov_b32_e32 v5, v0
	v_mov_b32_e32 v6, v0
	v_mov_b32_e32 v7, v0
	v_mov_b32_e32 v8, v0
	v_mov_b32_e32 v9, v0
	v_mov_b32_e32 v10, v0
	v_mov_b32_e32 v11, v0
	v_mov_b32_e32 v12, v0
	v_mov_b32_e32 v13, v0
	s_waitcnt vmcnt(7)
	v_lshlrev_b32_e32 v36, 16, v16
	v_and_b32_e32 v37, 0xffff0000, v16
	v_lshlrev_b32_e32 v16, 16, v17
	v_and_b32_e32 v17, 0xffff0000, v17
	v_pk_mul_f32 v[16:17], v[16:17], s[74:75] op_sel_hi:[1,0]
	v_pk_mul_f32 v[32:33], v[36:37], s[74:75] op_sel_hi:[1,0]
	v_cvt_pk_bf16_f32 v105, v16, v17
	v_lshlrev_b32_e32 v16, 16, v18
	v_and_b32_e32 v17, 0xffff0000, v18
	v_pk_mul_f32 v[16:17], v[16:17], s[74:75] op_sel_hi:[1,0]
	v_cvt_pk_bf16_f32 v104, v32, v33
	v_cvt_pk_bf16_f32 v106, v16, v17
	v_lshlrev_b32_e32 v16, 16, v19
	v_and_b32_e32 v17, 0xffff0000, v19
	v_pk_mul_f32 v[16:17], v[16:17], s[74:75] op_sel_hi:[1,0]
	v_and_b32_e32 v178, 0xc0, v40
	v_cvt_pk_bf16_f32 v107, v16, v17
	s_waitcnt vmcnt(6)
; template <bool DIFF>
; __device__ __forceinline__ void attn_item(const Params& p, int l, int I, LAS unsigned char* lds, const int tid) {
;     ...
;     float zf = 0.f; asm volatile("" : "+v"(zf));
; #pragma unroll
;     for (int r = 0; r < 16; ++r) { o1[0][r] = zf; o1[1][r] = zf; o2[0][r] = zf; o2[1][r] = zf; }
;     const float sc = (DIFF ? 0.17677669529663687f : 0.10206207261596575f) * LOG2E;
; #pragma unroll
;     for (int d0 = 0; d0 < (DIFF ? 4 : 6); ++d0) qf[d0] = scale_bf8(qf[d0], sc);
;     f32x16 negm1, negm2;
; #pragma unroll
;     for (int r = 0; r < 16; ++r) { negm1[r] = zf; negm2[r] = zf; }
;     const unsigned vlane = ((lane >> 4) & 1) * 32 + (lane & 3) * 8 + (4 * hi + ((lane & 15) >> 2)) * 64;
;     gload(0, 0); gload(1, 1); lwrite(0, 0); lwrite(0, 1);
;     __syncthreads();
;     for (int st = 0; st < nt / 2; ++st) {
	v_lshlrev_b32_e32 v16, 16, v20
	v_and_b32_e32 v17, 0xffff0000, v20
	v_pk_mul_f32 v[16:17], v[16:17], s[74:75] op_sel_hi:[1,0]
	v_lshl_add_u64 v[166:167], s[4:5], 0, v[38:39]
	v_cvt_pk_bf16_f32 v112, v16, v17
	v_lshlrev_b32_e32 v16, 16, v21
	v_and_b32_e32 v17, 0xffff0000, v21
	v_pk_mul_f32 v[16:17], v[16:17], s[74:75] op_sel_hi:[1,0]
	v_mov_b64_e32 v[62:63], v[14:15]
	v_cvt_pk_bf16_f32 v113, v16, v17
	v_lshlrev_b32_e32 v16, 16, v22
	v_and_b32_e32 v17, 0xffff0000, v22
	v_pk_mul_f32 v[16:17], v[16:17], s[74:75] op_sel_hi:[1,0]
	s_mov_b32 s34, 0
	v_cvt_pk_bf16_f32 v114, v16, v17
	v_lshlrev_b32_e32 v16, 16, v23
	v_and_b32_e32 v17, 0xffff0000, v23
	v_pk_mul_f32 v[16:17], v[16:17], s[74:75] op_sel_hi:[1,0]
	v_lshlrev_b32_e32 v177, 8, v171
	v_cvt_pk_bf16_f32 v115, v16, v17
	s_waitcnt vmcnt(5)
	v_lshlrev_b32_e32 v16, 16, v24
	v_and_b32_e32 v17, 0xffff0000, v24
	v_pk_mul_f32 v[16:17], v[16:17], s[74:75] op_sel_hi:[1,0]
	v_lshlrev_b32_e32 v181, 10, v171
	v_cvt_pk_bf16_f32 v120, v16, v17
	v_lshlrev_b32_e32 v16, 16, v25
	v_and_b32_e32 v17, 0xffff0000, v25
	v_pk_mul_f32 v[16:17], v[16:17], s[74:75] op_sel_hi:[1,0]
	v_lshlrev_b32_e32 v182, 4, v170
	v_cvt_pk_bf16_f32 v121, v16, v17
	v_lshlrev_b32_e32 v16, 16, v26
	v_and_b32_e32 v17, 0xffff0000, v26
	v_pk_mul_f32 v[16:17], v[16:17], s[74:75] op_sel_hi:[1,0]
	v_cmp_gt_u32_e64 s[4:5], 32, v168
	v_cvt_pk_bf16_f32 v122, v16, v17
	v_lshlrev_b32_e32 v16, 16, v27
	v_and_b32_e32 v17, 0xffff0000, v27
	v_pk_mul_f32 v[16:17], v[16:17], s[74:75] op_sel_hi:[1,0]
	v_lshl_add_u32 v180, v170, 2, s35
	v_cvt_pk_bf16_f32 v123, v16, v17
	s_waitcnt vmcnt(4)
	v_lshlrev_b32_e32 v16, 16, v28
	v_and_b32_e32 v17, 0xffff0000, v28
	v_pk_mul_f32 v[16:17], v[16:17], s[74:75] op_sel_hi:[1,0]
	s_addk_i32 s36, 0xff00
	v_cvt_pk_bf16_f32 v124, v16, v17
	v_lshlrev_b32_e32 v16, 16, v29
	v_and_b32_e32 v17, 0xffff0000, v29
	v_pk_mul_f32 v[16:17], v[16:17], s[74:75] op_sel_hi:[1,0]
	s_add_i32 s37, s37, 0x80c0
	v_cvt_pk_bf16_f32 v125, v16, v17
	v_lshlrev_b32_e32 v16, 16, v30
	v_and_b32_e32 v17, 0xffff0000, v30
	v_pk_mul_f32 v[16:17], v[16:17], s[74:75] op_sel_hi:[1,0]
	v_add_u32_e32 v183, 0x80, v172
	v_cvt_pk_bf16_f32 v126, v16, v17
	v_lshlrev_b32_e32 v16, 16, v31
	v_and_b32_e32 v17, 0xffff0000, v31
	v_pk_mul_f32 v[16:17], v[16:17], s[74:75] op_sel_hi:[1,0]
	v_or_b32_e32 v184, 0x80, v173
	v_cvt_pk_bf16_f32 v127, v16, v17
	v_lshlrev_b32_e32 v16, 1, v169
	v_lshl_add_u32 v17, v172, 6, v41
	v_and_b32_e32 v175, 32, v16
	v_lshlrev_b32_e32 v16, 3, v169
	v_and_or_b32 v179, v40, 48, v17
	v_and_b32_e32 v176, 24, v16
	v_add_u32_e32 v16, 0, v174
	v_add_u32_e32 v17, 0, v179
	s_waitcnt vmcnt(1)
	ds_write_b128 v16, v[96:99]
	ds_write_b128 v17, v[100:103] offset:12288
	ds_write_b128 v16, v[108:111] offset:20480
	s_waitcnt vmcnt(0)
	ds_write_b128 v17, v[116:119] offset:32768
	v_mov_b64_e32 v[30:31], v[14:15]
	v_mov_b64_e32 v[46:47], v[14:15]
	v_mov_b32_e32 v161, 0
	v_mov_b64_e32 v[28:29], v[12:13]
	v_mov_b64_e32 v[26:27], v[10:11]
	v_mov_b64_e32 v[24:25], v[8:9]
	v_mov_b64_e32 v[22:23], v[6:7]
	v_mov_b64_e32 v[20:21], v[4:5]
	v_mov_b64_e32 v[18:19], v[2:3]
	v_mov_b64_e32 v[16:17], v[0:1]
	v_mov_b64_e32 v[44:45], v[12:13]
	v_mov_b64_e32 v[42:43], v[10:11]
	v_mov_b64_e32 v[40:41], v[8:9]
	v_mov_b64_e32 v[38:39], v[6:7]
	v_mov_b64_e32 v[36:37], v[4:5]
	v_mov_b64_e32 v[34:35], v[2:3]
	v_mov_b64_e32 v[32:33], v[0:1]
	v_mov_b64_e32 v[60:61], v[12:13]
	v_mov_b64_e32 v[58:59], v[10:11]
	v_mov_b64_e32 v[56:57], v[8:9]
	v_mov_b64_e32 v[54:55], v[6:7]
	v_mov_b64_e32 v[52:53], v[4:5]
	v_mov_b64_e32 v[50:51], v[2:3]
	v_mov_b64_e32 v[48:49], v[0:1]
	v_add_u32_e32 v181, v181, v182
	v_add3_u32 v184, v175, v176, v177
	v_add_u32_e32 v184, v184, v178
	v_mov_b32_e32 v178, v174
	v_lshlrev_b32_e32 v176, 10, v173
	v_mov_b32_e32 v177, 0
	v_lshl_add_u64 v[176:177], v[164:165], 0, v[176:177]
	v_lshlrev_b32_e32 v182, 10, v172
	v_mov_b32_e32 v183, 0
	v_lshl_add_u64 v[182:183], v[166:167], 0, v[182:183]
	v_mov_b32_e32 v194, 0
	v_mov_b32_e32 v195, 0
	v_mov_b32_e32 v196, 0
	v_mov_b32_e32 v197, 0
	v_mov_b32_e32 v198, 0
	v_mov_b32_e32 v199, 0
	v_mov_b32_e32 v200, 0
	v_mov_b32_e32 v201, 0
	v_mov_b32_e32 v202, 0
	v_mov_b32_e32 v203, 0
	v_mov_b32_e32 v204, 0
	v_mov_b32_e32 v205, 0
	v_mov_b32_e32 v206, 0
	v_mov_b32_e32 v207, 0
	v_mov_b32_e32 v208, 0
	v_mov_b32_e32 v209, 0
	v_mov_b32_e32 v218, 0
	v_mov_b32_e32 v219, 0
	v_mov_b32_e32 v220, 0
	v_mov_b32_e32 v221, 0
	v_mov_b32_e32 v222, 0
	v_mov_b32_e32 v223, 0
	v_mov_b32_e32 v224, 0
	v_mov_b32_e32 v225, 0
	v_mov_b32_e32 v226, 0
	v_mov_b32_e32 v227, 0
	v_mov_b32_e32 v228, 0
	v_mov_b32_e32 v229, 0
	v_mov_b32_e32 v230, 0
	v_mov_b32_e32 v231, 0
	v_mov_b32_e32 v232, 0
	v_mov_b32_e32 v233, 0
	v_mov_b32_e32 v185, 0
	v_mov_b32_e32 v162, 0
	v_mov_b32_e32 v186, 0
	s_waitcnt lgkmcnt(0)
	s_barrier
	s_branch .LBB0_493

; __device__ __forceinline__ unsigned cvt_pk_bf16(float lo, float hi) { const f32x2 v = {lo, hi}; const bf16x2_t b = __builtin_convertvector(v, bf16x2_t); return __builtin_bit_cast(unsigned, b); }
; __device__ __forceinline__ void softmax_pv(f32x16& s0, f32x16& s1, float& mref, f32x16& negm, float& lsum, f32x16 (&o)[2], LAS float* fac, const bf16x8 (&vf)[2][4], bool first, int r32, int hi) {
;     ...
;     float ps0 = 0.f, ps1 = 0.f;
; #pragma unroll
;     for (int r = 0; r < 16; ++r) { s0[r] = __builtin_amdgcn_exp2f(s0[r]); s1[r] = __builtin_amdgcn_exp2f(s1[r]); ps0 += s0[r]; ps1 += s1[r]; }
;     lsum += ps0 + ps1;
;     bf16x8 pa[4];
; #pragma unroll
;     for (int k = 0; k < 4; ++k) {
;         const f32x16& s = (k < 2) ? s0 : s1; const int rb = 8 * (k & 1);
;         u32x4 w; w.x = cvt_pk_bf16(s[rb + 0], s[rb + 1]); w.y = cvt_pk_bf16(s[rb + 2], s[rb + 3]); w.z = cvt_pk_bf16(s[rb + 4], s[rb + 5]); w.w = cvt_pk_bf16(s[rb + 6], s[rb + 7]);
;         pa[k] = __builtin_bit_cast(bf16x8, w);
;     }
; #pragma unroll
;     for (int k = 0; k < 4; ++k) {
;         o[0] = __builtin_amdgcn_mfma_f32_32x32x16_bf16(pa[k], vf[0][k], o[0], 0, 0, 0);
;         o[1] = __builtin_amdgcn_mfma_f32_32x32x16_bf16(pa[k], vf[1][k], o[1], 0, 0, 0);
;     }
.Ldr_cont_00:
	v_exp_f32_e32 v80, v80
	v_exp_f32_e32 v81, v81
	v_mfma_f32_32x32x16_bf16 v[64:79], v[238:241], v[104:107], v[194:209]
	v_exp_f32_e32 v82, v82
	v_exp_f32_e32 v83, v83
	v_exp_f32_e32 v84, v84
	v_mfma_f32_32x32x16_bf16 v[64:79], v[188:191], v[112:115], v[64:79]
	v_exp_f32_e32 v85, v85
	v_exp_f32_e32 v86, v86
	v_exp_f32_e32 v87, v87
	v_cvt_pk_bf16_f32 v210, v80, v81
	v_cvt_pk_bf16_f32 v211, v82, v83
	v_cvt_pk_bf16_f32 v212, v84, v85
	v_cvt_pk_bf16_f32 v213, v86, v87
	v_add_f32_e32 v214, v80, v82
	v_add_f32_e32 v215, v81, v83
	v_add_f32_e32 v214, v214, v84
	v_add_f32_e32 v215, v215, v85
	v_add_f32_e32 v214, v214, v86
	v_add_f32_e32 v215, v215, v87
.Ldr_join_00:
	ds_read_b128 v[234:237], v187 offset:4096
	ds_read_b128 v[238:241], v187 offset:4608
	ds_read_b128 v[242:245], v187 offset:6144
	ds_read_b128 v[188:191], v187 offset:6656
	s_waitcnt lgkmcnt(7)
	ds_read_b64_tr_b16 v[136:137], v163 offset:14336
	ds_read_b64_tr_b16 v[138:139], v163 offset:14848
	ds_read_b64_tr_b16 v[152:153], v163 offset:18432
	ds_read_b64_tr_b16 v[154:155], v163 offset:18944
	ds_read_b64_tr_b16 v[140:141], v163 offset:15360
	ds_read_b64_tr_b16 v[142:143], v163 offset:15872
	ds_read_b64_tr_b16 v[156:157], v163 offset:19456
	ds_read_b64_tr_b16 v[158:159], v163 offset:19968
	v_exp_f32_e32 v88, v88
	v_exp_f32_e32 v89, v89
	v_exp_f32_e32 v90, v90
	v_mfma_f32_32x32x16_bf16 v[32:47], v[210:213], v[128:131], v[32:47]
	v_exp_f32_e32 v91, v91
	v_exp_f32_e32 v92, v92
	v_mfma_f32_32x32x16_bf16 v[48:63], v[210:213], v[144:147], v[48:63]
	v_exp_f32_e32 v93, v93
	v_exp_f32_e32 v94, v94
	v_exp_f32_e32 v95, v95
	v_cvt_pk_bf16_f32 v248, v88, v89
	v_cvt_pk_bf16_f32 v249, v90, v91
	v_cvt_pk_bf16_f32 v250, v92, v93
	v_cvt_pk_bf16_f32 v251, v94, v95
	v_add_f32_e32 v214, v214, v88
	v_add_f32_e32 v215, v215, v89
	v_add_f32_e32 v214, v214, v90
	v_add_f32_e32 v215, v215, v91
	v_add_f32_e32 v214, v214, v92
	v_add_f32_e32 v215, v215, v93
	v_add_f32_e32 v214, v214, v94
	v_add_f32_e32 v215, v215, v95
	v_exp_f32_e32 v64, v64
	v_exp_f32_e32 v65, v65
	s_waitcnt lgkmcnt(12)
	v_mfma_f32_32x32x16_bf16 v[32:47], v[248:251], v[132:135], v[32:47]
	v_exp_f32_e32 v66, v66
	v_exp_f32_e32 v67, v67
	v_mfma_f32_32x32x16_bf16 v[48:63], v[248:251], v[148:151], v[48:63]
	v_exp_f32_e32 v68, v68
	v_exp_f32_e32 v69, v69
	s_waitcnt lgkmcnt(8)
	v_mfma_f32_32x32x16_bf16 v[80:95], v[234:237], v[120:123], v[218:233]
	v_exp_f32_e32 v70, v70
	v_exp_f32_e32 v71, v71
	v_cvt_pk_bf16_f32 v210, v64, v65
	v_cvt_pk_bf16_f32 v211, v66, v67
	v_cvt_pk_bf16_f32 v212, v68, v69
	v_cvt_pk_bf16_f32 v213, v70, v71
	v_add_f32_e32 v214, v214, v64
	v_add_f32_e32 v215, v215, v65
	v_add_f32_e32 v214, v214, v66
	v_add_f32_e32 v215, v215, v67
	v_add_f32_e32 v214, v214, v68
	v_add_f32_e32 v215, v215, v69
	v_add_f32_e32 v214, v214, v70
	v_add_f32_e32 v215, v215, v71
	v_exp_f32_e32 v72, v72
	v_exp_f32_e32 v73, v73
	v_mfma_f32_32x32x16_bf16 v[80:95], v[242:245], v[124:127], v[80:95]
	v_exp_f32_e32 v74, v74
	v_exp_f32_e32 v75, v75
	s_waitcnt lgkmcnt(4)
	v_mfma_f32_32x32x16_bf16 v[32:47], v[210:213], v[136:139], v[32:47]
	v_exp_f32_e32 v76, v76
	v_exp_f32_e32 v77, v77
	v_mfma_f32_32x32x16_bf16 v[48:63], v[210:213], v[152:155], v[48:63]
	v_exp_f32_e32 v78, v78
	v_exp_f32_e32 v79, v79
	v_cvt_pk_bf16_f32 v248, v72, v73
	v_cvt_pk_bf16_f32 v249, v74, v75
	v_cvt_pk_bf16_f32 v250, v76, v77
	v_cvt_pk_bf16_f32 v251, v78, v79
	v_add_f32_e32 v214, v214, v72
	v_add_f32_e32 v215, v215, v73
	v_add_f32_e32 v214, v214, v74
	v_add_f32_e32 v215, v215, v75
	v_add_f32_e32 v214, v214, v76
	v_add_f32_e32 v215, v215, v77
	v_add_f32_e32 v214, v214, v78
	v_add_f32_e32 v215, v215, v79
	v_add_f32_e32 v214, v214, v215
	v_add_f32_e32 v162, v162, v214
	s_cmp_eq_u32 s34, 0
	s_cbranch_scc1 .Ldr_first_01
.Ldr_cont_01:
	v_exp_f32_e32 v80, v80
	v_mfma_f32_32x32x16_bf16 v[64:79], v[238:241], v[120:123], v[218:233]
	v_exp_f32_e32 v81, v81
	v_mfma_f32_32x32x16_bf16 v[64:79], v[188:191], v[124:127], v[64:79]
	v_exp_f32_e32 v82, v82
	v_exp_f32_e32 v83, v83
	s_waitcnt lgkmcnt(0)
	v_mfma_f32_32x32x16_bf16 v[32:47], v[248:251], v[140:143], v[32:47]
	v_exp_f32_e32 v84, v84
	v_exp_f32_e32 v85, v85
	v_mfma_f32_32x32x16_bf16 v[48:63], v[248:251], v[156:159], v[48:63]
	v_exp_f32_e32 v86, v86
	v_exp_f32_e32 v87, v87
	v_cvt_pk_bf16_f32 v210, v80, v81
	v_cvt_pk_bf16_f32 v211, v82, v83
	v_cvt_pk_bf16_f32 v212, v84, v85
	v_cvt_pk_bf16_f32 v213, v86, v87
	v_add_f32_e32 v214, v80, v82
	v_add_f32_e32 v215, v81, v83
	v_add_f32_e32 v214, v214, v84
	v_add_f32_e32 v215, v215, v85
	v_add_f32_e32 v214, v214, v86
	v_add_f32_e32 v215, v215, v87
; #define LAS __attribute__((address_space(3)))
; __device__ __forceinline__ unsigned cvt_pk_bf16(float lo, float hi) { const f32x2 v = {lo, hi}; const bf16x2_t b = __builtin_convertvector(v, bf16x2_t); return __builtin_bit_cast(unsigned, b); }
; __device__ __forceinline__ void softmax_pv(f32x16& s0, f32x16& s1, float& mref, f32x16& negm, float& lsum, f32x16 (&o)[2], LAS float* fac, const bf16x8 (&vf)[2][4], bool first, int r32, int hi) {
;     ...
;     float ps0 = 0.f, ps1 = 0.f;
; #pragma unroll
;     for (int r = 0; r < 16; ++r) { s0[r] = __builtin_amdgcn_exp2f(s0[r]); s1[r] = __builtin_amdgcn_exp2f(s1[r]); ps0 += s0[r]; ps1 += s1[r]; }
;     lsum += ps0 + ps1;
;     bf16x8 pa[4];
; #pragma unroll
;     for (int k = 0; k < 4; ++k) {
;         const f32x16& s = (k < 2) ? s0 : s1; const int rb = 8 * (k & 1);
;         u32x4 w; w.x = cvt_pk_bf16(s[rb + 0], s[rb + 1]); w.y = cvt_pk_bf16(s[rb + 2], s[rb + 3]); w.z = cvt_pk_bf16(s[rb + 4], s[rb + 5]); w.w = cvt_pk_bf16(s[rb + 6], s[rb + 7]);
;         pa[k] = __builtin_bit_cast(bf16x8, w);
;     }
; #pragma unroll
;     for (int k = 0; k < 4; ++k) {
;         o[0] = __builtin_amdgcn_mfma_f32_32x32x16_bf16(pa[k], vf[0][k], o[0], 0, 0, 0);
;         o[1] = __builtin_amdgcn_mfma_f32_32x32x16_bf16(pa[k], vf[1][k], o[1], 0, 0, 0);
;     }
; template <bool DIFF>
; __device__ __forceinline__ void attn_item(const Params& p, int l, int I, LAS unsigned char* lds, const int tid) {
;     ...
;             bf16x8 kg[2][2];
; #pragma unroll
;             for (int d0 = 0; d0 < 2; ++d0) { kg[d0][0] = *(const LAS bf16x8*)(kb + 4096 + d0 * 2048); kg[d0][1] = *(const LAS bf16x8*)(kb + 4096 + d0 * 2048 + 512); }
; #pragma unroll
;             for (int d0 = 0; d0 < 2; ++d0) {
;                 s0 = __builtin_amdgcn_mfma_f32_32x32x16_bf16(kg[d0][0], qf[2 + d0], s0, 0, 0, 0);
;                 s1 = __builtin_amdgcn_mfma_f32_32x32x16_bf16(kg[d0][1], qf[2 + d0], s1, 0, 0, 0);
;             }
;             softmax_pv(s0, s1, mref2, negm2, l2, o2, scr + 32, vf, t == 0, r32, hi);
.Ldr_join_01:
	ds_read_b128 v[234:237], v187 offset:20480
	ds_read_b128 v[238:241], v187 offset:20992
	ds_read_b128 v[242:245], v187 offset:22528
	ds_read_b128 v[188:191], v187 offset:23040
	v_exp_f32_e32 v88, v88
	v_exp_f32_e32 v89, v89
	v_exp_f32_e32 v90, v90
	v_mfma_f32_32x32x16_bf16 v[0:15], v[210:213], v[128:131], v[0:15]
	v_exp_f32_e32 v91, v91
	v_exp_f32_e32 v92, v92
	v_mfma_f32_32x32x16_bf16 v[16:31], v[210:213], v[144:147], v[16:31]
	v_exp_f32_e32 v93, v93
	v_exp_f32_e32 v94, v94
	v_exp_f32_e32 v95, v95
	v_cvt_pk_bf16_f32 v248, v88, v89
	v_cvt_pk_bf16_f32 v249, v90, v91
	v_cvt_pk_bf16_f32 v250, v92, v93
	v_cvt_pk_bf16_f32 v251, v94, v95
	v_add_f32_e32 v214, v214, v88
	v_add_f32_e32 v215, v215, v89
	v_add_f32_e32 v214, v214, v90
	v_add_f32_e32 v215, v215, v91
	v_add_f32_e32 v214, v214, v92
	v_add_f32_e32 v215, v215, v93
	v_add_f32_e32 v214, v214, v94
	v_add_f32_e32 v215, v215, v95
	v_exp_f32_e32 v64, v64
	v_exp_f32_e32 v65, v65
	v_mfma_f32_32x32x16_bf16 v[0:15], v[248:251], v[132:135], v[0:15]
	v_exp_f32_e32 v66, v66
	v_exp_f32_e32 v67, v67
	v_mfma_f32_32x32x16_bf16 v[16:31], v[248:251], v[148:151], v[16:31]
	v_exp_f32_e32 v68, v68
	v_exp_f32_e32 v69, v69
	s_waitcnt lgkmcnt(0)
	v_mfma_f32_32x32x16_bf16 v[80:95], v[234:237], v[104:107], v[194:209]
	v_exp_f32_e32 v70, v70
	v_exp_f32_e32 v71, v71
	v_cvt_pk_bf16_f32 v210, v64, v65
	v_cvt_pk_bf16_f32 v211, v66, v67
	v_cvt_pk_bf16_f32 v212, v68, v69
	v_cvt_pk_bf16_f32 v213, v70, v71
	v_add_f32_e32 v214, v214, v64
	v_add_f32_e32 v215, v215, v65
	v_add_f32_e32 v214, v214, v66
	v_add_f32_e32 v215, v215, v67
	v_add_f32_e32 v214, v214, v68
	v_add_f32_e32 v215, v215, v69
	v_add_f32_e32 v214, v214, v70
	v_add_f32_e32 v215, v215, v71
	v_exp_f32_e32 v72, v72
	v_exp_f32_e32 v73, v73
	v_mfma_f32_32x32x16_bf16 v[80:95], v[242:245], v[112:115], v[80:95]
	v_exp_f32_e32 v74, v74
	v_exp_f32_e32 v75, v75
	v_mfma_f32_32x32x16_bf16 v[0:15], v[210:213], v[136:139], v[0:15]
	v_exp_f32_e32 v76, v76
	v_exp_f32_e32 v77, v77
	v_mfma_f32_32x32x16_bf16 v[16:31], v[210:213], v[152:155], v[16:31]
	v_exp_f32_e32 v78, v78
	v_exp_f32_e32 v79, v79
	v_cvt_pk_bf16_f32 v248, v72, v73
	v_cvt_pk_bf16_f32 v249, v74, v75
	v_cvt_pk_bf16_f32 v250, v76, v77
	v_cvt_pk_bf16_f32 v251, v78, v79
	v_add_f32_e32 v214, v214, v72
	v_add_f32_e32 v215, v215, v73
	v_add_f32_e32 v214, v214, v74
	v_add_f32_e32 v215, v215, v75
	v_add_f32_e32 v214, v214, v76
	v_add_f32_e32 v215, v215, v77
	v_add_f32_e32 v214, v214, v78
	v_add_f32_e32 v215, v215, v79
	v_add_f32_e32 v214, v214, v215
	v_add_f32_e32 v161, v161, v214
	ds_read_b64_tr_b16 v[128:129], v163 offset:32768
	ds_read_b64_tr_b16 v[130:131], v163 offset:33280
	ds_read_b64_tr_b16 v[144:145], v163 offset:36864
	ds_read_b64_tr_b16 v[146:147], v163 offset:37376
	ds_read_b64_tr_b16 v[132:133], v163 offset:33792
	ds_read_b64_tr_b16 v[134:135], v163 offset:34304
	ds_read_b64_tr_b16 v[148:149], v163 offset:37888
	ds_read_b64_tr_b16 v[150:151], v163 offset:38400
	v_exp_f32_e32 v80, v80
	v_mfma_f32_32x32x16_bf16 v[64:79], v[238:241], v[104:107], v[194:209]
	v_exp_f32_e32 v81, v81
	v_mfma_f32_32x32x16_bf16 v[64:79], v[188:191], v[112:115], v[64:79]
	v_exp_f32_e32 v82, v82
	v_exp_f32_e32 v83, v83
	v_mfma_f32_32x32x16_bf16 v[0:15], v[248:251], v[140:143], v[0:15]
	v_exp_f32_e32 v84, v84
	v_exp_f32_e32 v85, v85
	v_mfma_f32_32x32x16_bf16 v[16:31], v[248:251], v[156:159], v[16:31]
	v_exp_f32_e32 v86, v86
	v_exp_f32_e32 v87, v87
	v_cvt_pk_bf16_f32 v210, v80, v81
	v_cvt_pk_bf16_f32 v211, v82, v83
	v_cvt_pk_bf16_f32 v212, v84, v85
	v_cvt_pk_bf16_f32 v213, v86, v87
	v_add_f32_e32 v214, v80, v82
	v_add_f32_e32 v215, v81, v83
	v_add_f32_e32 v214, v214, v84
	v_add_f32_e32 v215, v215, v85
	v_add_f32_e32 v214, v214, v86
	v_add_f32_e32 v215, v215, v87
	ds_read_b128 v[234:237], v187 offset:24576
	ds_read_b128 v[238:241], v187 offset:25088
	ds_read_b128 v[242:245], v187 offset:26624
	ds_read_b128 v[188:191], v187 offset:27136
	s_waitcnt lgkmcnt(7)
	ds_read_b64_tr_b16 v[136:137], v163 offset:34816
	ds_read_b64_tr_b16 v[138:139], v163 offset:35328
	ds_read_b64_tr_b16 v[152:153], v163 offset:38912
	ds_read_b64_tr_b16 v[154:155], v163 offset:39424
	ds_read_b64_tr_b16 v[140:141], v163 offset:35840
	ds_read_b64_tr_b16 v[142:143], v163 offset:36352
	ds_read_b64_tr_b16 v[156:157], v163 offset:39936
	ds_read_b64_tr_b16 v[158:159], v163 offset:40448
	v_exp_f32_e32 v88, v88
	v_exp_f32_e32 v89, v89
	v_exp_f32_e32 v90, v90
	v_mfma_f32_32x32x16_bf16 v[32:47], v[210:213], v[128:131], v[32:47]
	v_exp_f32_e32 v91, v91
	v_exp_f32_e32 v92, v92
	v_mfma_f32_32x32x16_bf16 v[48:63], v[210:213], v[144:147], v[48:63]
	v_exp_f32_e32 v93, v93
	v_exp_f32_e32 v94, v94
	v_exp_f32_e32 v95, v95
	v_cvt_pk_bf16_f32 v248, v88, v89
	v_cvt_pk_bf16_f32 v249, v90, v91
	v_cvt_pk_bf16_f32 v250, v92, v93
	v_cvt_pk_bf16_f32 v251, v94, v95
	v_add_f32_e32 v214, v214, v88
	v_add_f32_e32 v215, v215, v89
	v_add_f32_e32 v214, v214, v90
	v_add_f32_e32 v215, v215, v91
	v_add_f32_e32 v214, v214, v92
	v_add_f32_e32 v215, v215, v93
	v_add_f32_e32 v214, v214, v94
	v_add_f32_e32 v215, v215, v95
	v_exp_f32_e32 v64, v64
	v_exp_f32_e32 v65, v65
	s_waitcnt lgkmcnt(12)
; __device__ __forceinline__ unsigned cvt_pk_bf16(float lo, float hi) { const f32x2 v = {lo, hi}; const bf16x2_t b = __builtin_convertvector(v, bf16x2_t); return __builtin_bit_cast(unsigned, b); }
; __device__ __forceinline__ int crow(int r, int hi) { return (r & 3) + 8 * (r >> 2) + 4 * hi; }
; __device__ __forceinline__ void softmax_pv(f32x16& s0, f32x16& s1, float& mref, f32x16& negm, float& lsum, f32x16 (&o)[2], LAS float* fac, const bf16x8 (&vf)[2][4], bool first, int r32, int hi) {
;     ...
;     if (__builtin_expect(first || __any(mx > 16.0f), 0)) {
;         const float d = first ? mx : fmaxf(mx, 0.f);
;         const float f = __builtin_amdgcn_exp2f(-d);
;         lsum *= f; mref += d;
; #pragma unroll
;         for (int r = 0; r < 16; ++r) { s0[r] -= d; s1[r] -= d; negm[r] = -mref; }
;         if (hi == 0) fac[r32] = f;
;         asm volatile("s_waitcnt lgkmcnt(0)" ::: "memory");
; #pragma unroll
;         for (int r = 0; r < 16; ++r) { const float ff = fac[crow(r, hi)]; o[0][r] *= ff; o[1][r] *= ff; }
;     }
;     float ps0 = 0.f, ps1 = 0.f;
; #pragma unroll
;     for (int r = 0; r < 16; ++r) { s0[r] = __builtin_amdgcn_exp2f(s0[r]); s1[r] = __builtin_amdgcn_exp2f(s1[r]); ps0 += s0[r]; ps1 += s1[r]; }
;     lsum += ps0 + ps1;
;     bf16x8 pa[4];
; #pragma unroll
;     for (int k = 0; k < 4; ++k) {
;         const f32x16& s = (k < 2) ? s0 : s1; const int rb = 8 * (k & 1);
;         u32x4 w; w.x = cvt_pk_bf16(s[rb + 0], s[rb + 1]); w.y = cvt_pk_bf16(s[rb + 2], s[rb + 3]); w.z = cvt_pk_bf16(s[rb + 4], s[rb + 5]); w.w = cvt_pk_bf16(s[rb + 6], s[rb + 7]);
;         pa[k] = __builtin_bit_cast(bf16x8, w);
;     }
; #pragma unroll
;     for (int k = 0; k < 4; ++k) {
;         o[0] = __builtin_amdgcn_mfma_f32_32x32x16_bf16(pa[k], vf[0][k], o[0], 0, 0, 0);
;         o[1] = __builtin_amdgcn_mfma_f32_32x32x16_bf16(pa[k], vf[1][k], o[1], 0, 0, 0);
;     }
	v_mfma_f32_32x32x16_bf16 v[32:47], v[248:251], v[132:135], v[32:47]
	v_exp_f32_e32 v66, v66
	v_exp_f32_e32 v67, v67
	v_mfma_f32_32x32x16_bf16 v[48:63], v[248:251], v[148:151], v[48:63]
	v_exp_f32_e32 v68, v68
	v_exp_f32_e32 v69, v69
	s_waitcnt lgkmcnt(8)
	v_mfma_f32_32x32x16_bf16 v[80:95], v[234:237], v[120:123], v[218:233]
	v_exp_f32_e32 v70, v70
	v_exp_f32_e32 v71, v71
	v_cvt_pk_bf16_f32 v210, v64, v65
	v_cvt_pk_bf16_f32 v211, v66, v67
	v_cvt_pk_bf16_f32 v212, v68, v69
	v_cvt_pk_bf16_f32 v213, v70, v71
	v_add_f32_e32 v214, v214, v64
	v_add_f32_e32 v215, v215, v65
	v_add_f32_e32 v214, v214, v66
	v_add_f32_e32 v215, v215, v67
	v_add_f32_e32 v214, v214, v68
	v_add_f32_e32 v215, v215, v69
	v_add_f32_e32 v214, v214, v70
	v_add_f32_e32 v215, v215, v71
	v_exp_f32_e32 v72, v72
	v_exp_f32_e32 v73, v73
	v_mfma_f32_32x32x16_bf16 v[80:95], v[242:245], v[124:127], v[80:95]
	v_exp_f32_e32 v74, v74
	v_exp_f32_e32 v75, v75
	s_waitcnt lgkmcnt(4)
	v_mfma_f32_32x32x16_bf16 v[32:47], v[210:213], v[136:139], v[32:47]
	v_exp_f32_e32 v76, v76
	v_exp_f32_e32 v77, v77
	v_mfma_f32_32x32x16_bf16 v[48:63], v[210:213], v[152:155], v[48:63]
	v_exp_f32_e32 v78, v78
	v_exp_f32_e32 v79, v79
	v_cvt_pk_bf16_f32 v248, v72, v73
	v_cvt_pk_bf16_f32 v249, v74, v75
	v_cvt_pk_bf16_f32 v250, v76, v77
	v_cvt_pk_bf16_f32 v251, v78, v79
	v_add_f32_e32 v214, v214, v72
	v_add_f32_e32 v215, v215, v73
	v_add_f32_e32 v214, v214, v74
	v_add_f32_e32 v215, v215, v75
	v_add_f32_e32 v214, v214, v76
	v_add_f32_e32 v215, v215, v77
	v_add_f32_e32 v214, v214, v78
	v_add_f32_e32 v215, v215, v79
	v_add_f32_e32 v214, v214, v215
	v_add_f32_e32 v162, v162, v214
	v_exp_f32_e32 v80, v80
	v_exp_f32_e32 v81, v81
	v_mfma_f32_32x32x16_bf16 v[64:79], v[238:241], v[120:123], v[218:233]
	v_exp_f32_e32 v82, v82
	v_exp_f32_e32 v83, v83
	v_mfma_f32_32x32x16_bf16 v[64:79], v[188:191], v[124:127], v[64:79]
	v_exp_f32_e32 v84, v84
	v_exp_f32_e32 v85, v85
	s_waitcnt lgkmcnt(0)
	v_mfma_f32_32x32x16_bf16 v[32:47], v[248:251], v[140:143], v[32:47]
	v_exp_f32_e32 v86, v86
	v_exp_f32_e32 v87, v87
	v_cvt_pk_bf16_f32 v210, v80, v81
	v_cvt_pk_bf16_f32 v211, v82, v83
	v_cvt_pk_bf16_f32 v212, v84, v85
	v_cvt_pk_bf16_f32 v213, v86, v87
	v_add_f32_e32 v214, v80, v82
	v_add_f32_e32 v215, v81, v83
	v_add_f32_e32 v214, v214, v84
	v_add_f32_e32 v215, v215, v85
	v_add_f32_e32 v214, v214, v86
	v_add_f32_e32 v215, v215, v87
	v_exp_f32_e32 v88, v88
	v_exp_f32_e32 v89, v89
	v_mfma_f32_32x32x16_bf16 v[48:63], v[248:251], v[156:159], v[48:63]
	v_exp_f32_e32 v90, v90
	v_exp_f32_e32 v91, v91
	v_mfma_f32_32x32x16_bf16 v[0:15], v[210:213], v[128:131], v[0:15]
	v_exp_f32_e32 v92, v92
	v_exp_f32_e32 v93, v93
	v_mfma_f32_32x32x16_bf16 v[16:31], v[210:213], v[144:147], v[16:31]
	v_exp_f32_e32 v94, v94
	v_exp_f32_e32 v95, v95
	v_cvt_pk_bf16_f32 v248, v88, v89
	v_cvt_pk_bf16_f32 v249, v90, v91
	v_cvt_pk_bf16_f32 v250, v92, v93
	v_cvt_pk_bf16_f32 v251, v94, v95
	v_add_f32_e32 v214, v214, v88
	v_add_f32_e32 v215, v215, v89
	v_add_f32_e32 v214, v214, v90
	v_add_f32_e32 v215, v215, v91
	v_add_f32_e32 v214, v214, v92
	v_add_f32_e32 v215, v215, v93
	v_add_f32_e32 v214, v214, v94
	v_add_f32_e32 v215, v215, v95
	v_exp_f32_e32 v64, v64
	v_exp_f32_e32 v65, v65
	v_exp_f32_e32 v66, v66
	v_mfma_f32_32x32x16_bf16 v[0:15], v[248:251], v[132:135], v[0:15]
	v_exp_f32_e32 v67, v67
	v_exp_f32_e32 v68, v68
	v_mfma_f32_32x32x16_bf16 v[16:31], v[248:251], v[148:151], v[16:31]
	v_exp_f32_e32 v69, v69
	v_exp_f32_e32 v70, v70
	v_exp_f32_e32 v71, v71
	v_cvt_pk_bf16_f32 v210, v64, v65
	v_cvt_pk_bf16_f32 v211, v66, v67
	v_cvt_pk_bf16_f32 v212, v68, v69
	v_cvt_pk_bf16_f32 v213, v70, v71
	v_add_f32_e32 v214, v214, v64
	v_add_f32_e32 v215, v215, v65
	v_add_f32_e32 v214, v214, v66
	v_add_f32_e32 v215, v215, v67
	v_add_f32_e32 v214, v214, v68
	v_add_f32_e32 v215, v215, v69
	v_add_f32_e32 v214, v214, v70
	v_add_f32_e32 v215, v215, v71
	v_exp_f32_e32 v72, v72
	v_exp_f32_e32 v73, v73
	v_exp_f32_e32 v74, v74
	v_mfma_f32_32x32x16_bf16 v[0:15], v[210:213], v[136:139], v[0:15]
	v_exp_f32_e32 v75, v75
	v_exp_f32_e32 v76, v76
	v_mfma_f32_32x32x16_bf16 v[16:31], v[210:213], v[152:155], v[16:31]
	v_exp_f32_e32 v77, v77
	v_exp_f32_e32 v78, v78
	v_exp_f32_e32 v79, v79
	v_cvt_pk_bf16_f32 v248, v72, v73
	v_cvt_pk_bf16_f32 v249, v74, v75
	v_cvt_pk_bf16_f32 v250, v76, v77
	v_cvt_pk_bf16_f32 v251, v78, v79
	v_add_f32_e32 v214, v214, v72
	v_add_f32_e32 v215, v215, v73
	v_add_f32_e32 v214, v214, v74
	v_add_f32_e32 v215, v215, v75
	v_add_f32_e32 v214, v214, v76
	v_add_f32_e32 v215, v215, v77
	v_add_f32_e32 v214, v214, v78
	v_add_f32_e32 v215, v215, v79
	v_add_f32_e32 v214, v214, v215
	v_add_f32_e32 v161, v161, v214
	v_mfma_f32_32x32x16_bf16 v[0:15], v[248:251], v[140:143], v[0:15]
	v_mfma_f32_32x32x16_bf16 v[16:31], v[248:251], v[156:159], v[16:31]
	v_max_f32_e32 v210, v162, v161
	v_cmp_lt_f32_e32 vcc, 0x47800000, v210
	s_cbranch_vccnz .Ldq

; __device__ __forceinline__ int crow(int r, int hi) { return (r & 3) + 8 * (r >> 2) + 4 * hi; }
; __device__ __forceinline__ float half_max(float m) { auto rr = __builtin_amdgcn_permlane32_swap(__float_as_uint(m), __float_as_uint(m), false, false); return fmaxf(__uint_as_float(rr[0]), __uint_as_float(rr[1])); }
; __device__ __forceinline__ void softmax_pv(f32x16& s0, f32x16& s1, float& mref, f32x16& negm, float& lsum, f32x16 (&o)[2], LAS float* fac, const bf16x8 (&vf)[2][4], bool first, int r32, int hi) {
;     float ma = fmaxf(fmaxf(s0[0], s0[1]), s0[2]), mb = fmaxf(fmaxf(s1[0], s1[1]), s1[2]);
; #pragma unroll
;     for (int r = 3; r < 15; r += 2) { ma = fmaxf(fmaxf(ma, s0[r]), s0[r + 1]); mb = fmaxf(fmaxf(mb, s1[r]), s1[r + 1]); }
;     float mx = fmaxf(fmaxf(ma, mb), fmaxf(s0[15], s1[15]));
;     mx = half_max(mx);
;     if (__builtin_expect(first || __any(mx > 16.0f), 0)) {
;         const float d = first ? mx : fmaxf(mx, 0.f);
;         const float f = __builtin_amdgcn_exp2f(-d);
;         lsum *= f; mref += d;
; #pragma unroll
;         for (int r = 0; r < 16; ++r) { s0[r] -= d; s1[r] -= d; negm[r] = -mref; }
;         if (hi == 0) fac[r32] = f;
;         asm volatile("s_waitcnt lgkmcnt(0)" ::: "memory");
; #pragma unroll
;         for (int r = 0; r < 16; ++r) { const float ff = fac[crow(r, hi)]; o[0][r] *= ff; o[1][r] *= ff; }
.Ldr_first_00:
	s_waitcnt lgkmcnt(0)
	v_mfma_f32_32x32x16_bf16 v[64:79], v[238:241], v[104:107], v[194:209]
	v_mfma_f32_32x32x16_bf16 v[64:79], v[188:191], v[112:115], v[64:79]
	s_nop 7
	s_nop 3
	v_max3_f32 v210, v80, v81, v82
	v_max3_f32 v211, v64, v65, v66
	v_max3_f32 v210, v210, v83, v84
	v_max3_f32 v211, v211, v67, v68
	v_max3_f32 v210, v210, v85, v86
	v_max3_f32 v211, v211, v69, v70
	v_max3_f32 v210, v210, v87, v88
	v_max3_f32 v211, v211, v71, v72
	v_max3_f32 v210, v210, v89, v90
	v_max3_f32 v211, v211, v73, v74
	v_max3_f32 v210, v210, v91, v92
	v_max3_f32 v211, v211, v75, v76
	v_max3_f32 v210, v210, v93, v94
	v_max3_f32 v211, v211, v77, v78
	v_max_f32_e32 v212, v95, v79
	v_max3_f32 v210, v210, v211, v212
	v_mov_b32_e32 v211, v210
	s_nop 1
	v_permlane32_swap_b32_e32 v210, v211
	v_max_f32_e32 v160, v210, v211
	v_exp_f32_e64 v246, -v160
	v_sub_f32_e32 v80, v80, v160
	v_sub_f32_e32 v64, v64, v160
	v_sub_f32_e32 v81, v81, v160
	v_sub_f32_e32 v65, v65, v160
	v_sub_f32_e32 v82, v82, v160
	v_sub_f32_e32 v66, v66, v160
	v_sub_f32_e32 v83, v83, v160
	v_sub_f32_e32 v67, v67, v160
	v_sub_f32_e32 v84, v84, v160
	v_sub_f32_e32 v68, v68, v160
	v_sub_f32_e32 v85, v85, v160
	v_sub_f32_e32 v69, v69, v160
	v_sub_f32_e32 v86, v86, v160
	v_sub_f32_e32 v70, v70, v160
	v_sub_f32_e32 v87, v87, v160
	v_sub_f32_e32 v71, v71, v160
	v_sub_f32_e32 v88, v88, v160
	v_sub_f32_e32 v72, v72, v160
	v_sub_f32_e32 v89, v89, v160
	v_sub_f32_e32 v73, v73, v160
	v_sub_f32_e32 v90, v90, v160
	v_sub_f32_e32 v74, v74, v160
	v_sub_f32_e32 v91, v91, v160
	v_sub_f32_e32 v75, v75, v160
	v_sub_f32_e32 v92, v92, v160
	v_sub_f32_e32 v76, v76, v160
	v_sub_f32_e32 v93, v93, v160
	v_sub_f32_e32 v77, v77, v160
	v_sub_f32_e32 v94, v94, v160
	v_sub_f32_e32 v78, v78, v160
	v_sub_f32_e32 v95, v95, v160
	v_sub_f32_e32 v79, v79, v160
	s_and_saveexec_b64 s[20:21], s[4:5]
	ds_write_b32 v180, v246
	s_or_b64 exec, exec, s[20:21]
	v_add_f32_e32 v186, v186, v160
	v_xor_b32_e32 v194, 0x80000000, v186
	v_mov_b32_e32 v195, v194
	v_mov_b32_e32 v196, v194
	v_mov_b32_e32 v197, v194
	v_mov_b32_e32 v198, v194
	v_mov_b32_e32 v199, v194
	v_mov_b32_e32 v200, v194
	v_mov_b32_e32 v201, v194
	v_mov_b32_e32 v202, v194
	v_mov_b32_e32 v203, v194
	v_mov_b32_e32 v204, v194
	v_mov_b32_e32 v205, v194
	v_mov_b32_e32 v206, v194
	v_mov_b32_e32 v207, v194
	v_mov_b32_e32 v208, v194
	v_mov_b32_e32 v209, v194
	s_waitcnt lgkmcnt(0)
	v_add_u32_e32 v160, s35, v192
	ds_read_b128 v[210:213], v160
	ds_read_b128 v[248:251], v160 offset:32
	s_waitcnt lgkmcnt(0)
	v_pk_mul_f32 v[32:33], v[32:33], v[210:211]
	v_pk_mul_f32 v[34:35], v[34:35], v[212:213]
	v_pk_mul_f32 v[36:37], v[36:37], v[248:249]
	v_pk_mul_f32 v[38:39], v[38:39], v[250:251]
	v_pk_mul_f32 v[48:49], v[48:49], v[210:211]
	v_pk_mul_f32 v[50:51], v[50:51], v[212:213]
	v_pk_mul_f32 v[52:53], v[52:53], v[248:249]
	v_pk_mul_f32 v[54:55], v[54:55], v[250:251]
	ds_read_b128 v[210:213], v160 offset:64
	ds_read_b128 v[248:251], v160 offset:96
	s_waitcnt lgkmcnt(0)
	v_pk_mul_f32 v[40:41], v[40:41], v[210:211]
	v_pk_mul_f32 v[42:43], v[42:43], v[212:213]
	v_pk_mul_f32 v[44:45], v[44:45], v[248:249]
	v_pk_mul_f32 v[46:47], v[46:47], v[250:251]
	v_pk_mul_f32 v[56:57], v[56:57], v[210:211]
	v_pk_mul_f32 v[58:59], v[58:59], v[212:213]
	v_pk_mul_f32 v[60:61], v[60:61], v[248:249]
	v_pk_mul_f32 v[62:63], v[62:63], v[250:251]
	v_exp_f32_e32 v80, v80
	v_exp_f32_e32 v81, v81
	v_exp_f32_e32 v82, v82
	v_exp_f32_e32 v83, v83
	v_exp_f32_e32 v84, v84
	v_exp_f32_e32 v85, v85
	v_exp_f32_e32 v86, v86
	v_exp_f32_e32 v87, v87
	v_cvt_pk_bf16_f32 v210, v80, v81
	v_cvt_pk_bf16_f32 v211, v82, v83
	v_cvt_pk_bf16_f32 v212, v84, v85
	v_cvt_pk_bf16_f32 v213, v86, v87
	v_add_f32_e32 v214, v80, v82
	v_add_f32_e32 v215, v81, v83
	v_add_f32_e32 v214, v214, v84
	v_add_f32_e32 v215, v215, v85
	v_add_f32_e32 v214, v214, v86
	v_add_f32_e32 v215, v215, v87
	s_branch .Ldr_join_00
.Ldr_first_01:
	s_waitcnt lgkmcnt(0)
	v_mfma_f32_32x32x16_bf16 v[64:79], v[238:241], v[120:123], v[218:233]
	v_mfma_f32_32x32x16_bf16 v[64:79], v[188:191], v[124:127], v[64:79]
	v_mfma_f32_32x32x16_bf16 v[32:47], v[248:251], v[140:143], v[32:47]
	v_mfma_f32_32x32x16_bf16 v[48:63], v[248:251], v[156:159], v[48:63]
	s_nop 7
	s_nop 3
	v_max3_f32 v210, v80, v81, v82
	v_max3_f32 v211, v64, v65, v66
	v_max3_f32 v210, v210, v83, v84
	v_max3_f32 v211, v211, v67, v68
	v_max3_f32 v210, v210, v85, v86
	v_max3_f32 v211, v211, v69, v70
	v_max3_f32 v210, v210, v87, v88
	v_max3_f32 v211, v211, v71, v72
	v_max3_f32 v210, v210, v89, v90
	v_max3_f32 v211, v211, v73, v74
	v_max3_f32 v210, v210, v91, v92
	v_max3_f32 v211, v211, v75, v76
	v_max3_f32 v210, v210, v93, v94
	v_max3_f32 v211, v211, v77, v78
	v_max_f32_e32 v212, v95, v79
	v_max3_f32 v210, v210, v211, v212
	v_mov_b32_e32 v211, v210
	s_nop 1
	v_permlane32_swap_b32_e32 v210, v211
	v_max_f32_e32 v160, v210, v211
	v_exp_f32_e64 v246, -v160
	v_sub_f32_e32 v80, v80, v160
	v_sub_f32_e32 v64, v64, v160
	v_sub_f32_e32 v81, v81, v160
	v_sub_f32_e32 v65, v65, v160
	v_sub_f32_e32 v82, v82, v160
	v_sub_f32_e32 v66, v66, v160
	v_sub_f32_e32 v83, v83, v160
	v_sub_f32_e32 v67, v67, v160
	v_sub_f32_e32 v84, v84, v160
	v_sub_f32_e32 v68, v68, v160
	v_sub_f32_e32 v85, v85, v160
	v_sub_f32_e32 v69, v69, v160
	v_sub_f32_e32 v86, v86, v160
	v_sub_f32_e32 v70, v70, v160
	v_sub_f32_e32 v87, v87, v160
	v_sub_f32_e32 v71, v71, v160
	v_sub_f32_e32 v88, v88, v160
	v_sub_f32_e32 v72, v72, v160
	v_sub_f32_e32 v89, v89, v160
	v_sub_f32_e32 v73, v73, v160
	v_sub_f32_e32 v90, v90, v160
	v_sub_f32_e32 v74, v74, v160
	v_sub_f32_e32 v91, v91, v160
	v_sub_f32_e32 v75, v75, v160
	v_sub_f32_e32 v92, v92, v160
	v_sub_f32_e32 v76, v76, v160
	v_sub_f32_e32 v93, v93, v160
	v_sub_f32_e32 v77, v77, v160
	v_sub_f32_e32 v94, v94, v160
	v_sub_f32_e32 v78, v78, v160
	v_sub_f32_e32 v95, v95, v160
	v_sub_f32_e32 v79, v79, v160
	s_and_saveexec_b64 s[20:21], s[4:5]
	ds_write_b32 v180, v246 offset:128
	s_or_b64 exec, exec, s[20:21]
	v_add_f32_e32 v185, v185, v160
	v_xor_b32_e32 v218, 0x80000000, v185
	v_mov_b32_e32 v219, v218
	v_mov_b32_e32 v220, v218
	v_mov_b32_e32 v221, v218
	v_mov_b32_e32 v222, v218
	v_mov_b32_e32 v223, v218
	v_mov_b32_e32 v224, v218
	v_mov_b32_e32 v225, v218
	v_mov_b32_e32 v226, v218
	v_mov_b32_e32 v227, v218
	v_mov_b32_e32 v228, v218
	v_mov_b32_e32 v229, v218
	v_mov_b32_e32 v230, v218
	v_mov_b32_e32 v231, v218
	v_mov_b32_e32 v232, v218
	v_mov_b32_e32 v233, v218
	s_waitcnt lgkmcnt(0)
; __device__ __forceinline__ int crow(int r, int hi) { return (r & 3) + 8 * (r >> 2) + 4 * hi; }
; __device__ __forceinline__ void softmax_pv(f32x16& s0, f32x16& s1, float& mref, f32x16& negm, float& lsum, f32x16 (&o)[2], LAS float* fac, const bf16x8 (&vf)[2][4], bool first, int r32, int hi) {
;     ...
;     if (__builtin_expect(first || __any(mx > 16.0f), 0)) {
;         const float d = first ? mx : fmaxf(mx, 0.f);
;         const float f = __builtin_amdgcn_exp2f(-d);
;         lsum *= f; mref += d;
; #pragma unroll
;         for (int r = 0; r < 16; ++r) { s0[r] -= d; s1[r] -= d; negm[r] = -mref; }
;         if (hi == 0) fac[r32] = f;
;         asm volatile("s_waitcnt lgkmcnt(0)" ::: "memory");
; #pragma unroll
;         for (int r = 0; r < 16; ++r) { const float ff = fac[crow(r, hi)]; o[0][r] *= ff; o[1][r] *= ff; }
	v_add_u32_e32 v160, s35, v192
	ds_read_b128 v[210:213], v160 offset:128
	ds_read_b128 v[248:251], v160 offset:160
	s_waitcnt lgkmcnt(0)
	v_pk_mul_f32 v[0:1], v[0:1], v[210:211]
	v_pk_mul_f32 v[2:3], v[2:3], v[212:213]
	v_pk_mul_f32 v[4:5], v[4:5], v[248:249]
	v_pk_mul_f32 v[6:7], v[6:7], v[250:251]
	v_pk_mul_f32 v[16:17], v[16:17], v[210:211]
	v_pk_mul_f32 v[18:19], v[18:19], v[212:213]
	v_pk_mul_f32 v[20:21], v[20:21], v[248:249]
	v_pk_mul_f32 v[22:23], v[22:23], v[250:251]
	ds_read_b128 v[210:213], v160 offset:192
	ds_read_b128 v[248:251], v160 offset:224
	s_waitcnt lgkmcnt(0)
	v_pk_mul_f32 v[8:9], v[8:9], v[210:211]
	v_pk_mul_f32 v[10:11], v[10:11], v[212:213]
	v_pk_mul_f32 v[12:13], v[12:13], v[248:249]
	v_pk_mul_f32 v[14:15], v[14:15], v[250:251]
	v_pk_mul_f32 v[24:25], v[24:25], v[210:211]
	v_pk_mul_f32 v[26:27], v[26:27], v[212:213]
	v_pk_mul_f32 v[28:29], v[28:29], v[248:249]
	v_pk_mul_f32 v[30:31], v[30:31], v[250:251]
	v_exp_f32_e32 v80, v80
	v_exp_f32_e32 v81, v81
	v_exp_f32_e32 v82, v82
	v_exp_f32_e32 v83, v83
	v_exp_f32_e32 v84, v84
	v_exp_f32_e32 v85, v85
	v_exp_f32_e32 v86, v86
	v_exp_f32_e32 v87, v87
	v_cvt_pk_bf16_f32 v210, v80, v81
	v_cvt_pk_bf16_f32 v211, v82, v83
	v_cvt_pk_bf16_f32 v212, v84, v85
	v_cvt_pk_bf16_f32 v213, v86, v87
	v_add_f32_e32 v214, v80, v82
	v_add_f32_e32 v215, v81, v83
	v_add_f32_e32 v214, v214, v84
	v_add_f32_e32 v215, v215, v85
	v_add_f32_e32 v214, v214, v86
	v_add_f32_e32 v215, v215, v87
	s_branch .Ldr_join_01
.Ldq:
	s_nop 7
	v_mov_b32_e32 v210, v162
	v_mov_b32_e32 v211, v210
	s_nop 1
	v_permlane32_swap_b32_e32 v210, v211
	v_add_f32_e32 v210, v210, v211
	v_log_f32_e32 v160, v210
	s_nop 0
	v_ceil_f32_e32 v160, v160
	v_max_f32_e32 v160, 0, v160
	v_exp_f32_e64 v246, -v160
	s_nop 7
	v_mul_f32_e32 v162, v162, v246
	s_and_saveexec_b64 s[20:21], s[4:5]
	ds_write_b32 v180, v246
	s_or_b64 exec, exec, s[20:21]
	v_add_f32_e32 v186, v186, v160
	v_xor_b32_e32 v194, 0x80000000, v186
	v_mov_b32_e32 v195, v194
	v_mov_b32_e32 v196, v194
	v_mov_b32_e32 v197, v194
	v_mov_b32_e32 v198, v194
	v_mov_b32_e32 v199, v194
	v_mov_b32_e32 v200, v194
	v_mov_b32_e32 v201, v194
	v_mov_b32_e32 v202, v194
	v_mov_b32_e32 v203, v194
	v_mov_b32_e32 v204, v194
	v_mov_b32_e32 v205, v194
	v_mov_b32_e32 v206, v194
	v_mov_b32_e32 v207, v194
	v_mov_b32_e32 v208, v194
	v_mov_b32_e32 v209, v194
	s_waitcnt lgkmcnt(0)
	v_add_u32_e32 v160, s35, v192
	ds_read_b128 v[210:213], v160
	ds_read_b128 v[248:251], v160 offset:32
	s_waitcnt lgkmcnt(0)
	v_pk_mul_f32 v[32:33], v[32:33], v[210:211]
	v_pk_mul_f32 v[34:35], v[34:35], v[212:213]
	v_pk_mul_f32 v[36:37], v[36:37], v[248:249]
	v_pk_mul_f32 v[38:39], v[38:39], v[250:251]
	v_pk_mul_f32 v[48:49], v[48:49], v[210:211]
	v_pk_mul_f32 v[50:51], v[50:51], v[212:213]
	v_pk_mul_f32 v[52:53], v[52:53], v[248:249]
	v_pk_mul_f32 v[54:55], v[54:55], v[250:251]
	ds_read_b128 v[210:213], v160 offset:64
	ds_read_b128 v[248:251], v160 offset:96
	s_waitcnt lgkmcnt(0)
	v_pk_mul_f32 v[40:41], v[40:41], v[210:211]
	v_pk_mul_f32 v[42:43], v[42:43], v[212:213]
	v_pk_mul_f32 v[44:45], v[44:45], v[248:249]
	v_pk_mul_f32 v[46:47], v[46:47], v[250:251]
	v_pk_mul_f32 v[56:57], v[56:57], v[210:211]
	v_pk_mul_f32 v[58:59], v[58:59], v[212:213]
	v_pk_mul_f32 v[60:61], v[60:61], v[248:249]
	v_pk_mul_f32 v[62:63], v[62:63], v[250:251]
	v_mov_b32_e32 v210, v161
	v_mov_b32_e32 v211, v210
	s_nop 1
	v_permlane32_swap_b32_e32 v210, v211
	v_add_f32_e32 v210, v210, v211
	v_log_f32_e32 v160, v210
	s_nop 0
	v_ceil_f32_e32 v160, v160
	v_max_f32_e32 v160, 0, v160
	v_exp_f32_e64 v246, -v160
	s_nop 7
	v_mul_f32_e32 v161, v161, v246
	s_and_saveexec_b64 s[20:21], s[4:5]
	ds_write_b32 v180, v246 offset:128
	s_or_b64 exec, exec, s[20:21]
	v_add_f32_e32 v185, v185, v160
	v_xor_b32_e32 v218, 0x80000000, v185
	v_mov_b32_e32 v219, v218
	v_mov_b32_e32 v220, v218
	v_mov_b32_e32 v221, v218
	v_mov_b32_e32 v222, v218
	v_mov_b32_e32 v223, v218
	v_mov_b32_e32 v224, v218
	v_mov_b32_e32 v225, v218
	v_mov_b32_e32 v226, v218
	v_mov_b32_e32 v227, v218
	v_mov_b32_e32 v228, v218
	v_mov_b32_e32 v229, v218
	v_mov_b32_e32 v230, v218
	v_mov_b32_e32 v231, v218
	v_mov_b32_e32 v232, v218
	v_mov_b32_e32 v233, v218
	s_waitcnt lgkmcnt(0)
	v_add_u32_e32 v160, s35, v192
	ds_read_b128 v[210:213], v160 offset:128
	ds_read_b128 v[248:251], v160 offset:160
	s_waitcnt lgkmcnt(0)
	v_pk_mul_f32 v[0:1], v[0:1], v[210:211]
	v_pk_mul_f32 v[2:3], v[2:3], v[212:213]
	v_pk_mul_f32 v[4:5], v[4:5], v[248:249]
	v_pk_mul_f32 v[6:7], v[6:7], v[250:251]
	v_pk_mul_f32 v[16:17], v[16:17], v[210:211]
	v_pk_mul_f32 v[18:19], v[18:19], v[212:213]
	v_pk_mul_f32 v[20:21], v[20:21], v[248:249]
	v_pk_mul_f32 v[22:23], v[22:23], v[250:251]
	ds_read_b128 v[210:213], v160 offset:192
	ds_read_b128 v[248:251], v160 offset:224
	s_waitcnt lgkmcnt(0)
	v_pk_mul_f32 v[8:9], v[8:9], v[210:211]
	v_pk_mul_f32 v[10:11], v[10:11], v[212:213]
	v_pk_mul_f32 v[12:13], v[12:13], v[248:249]
	v_pk_mul_f32 v[14:15], v[14:15], v[250:251]
	v_pk_mul_f32 v[24:25], v[24:25], v[210:211]
	v_pk_mul_f32 v[26:27], v[26:27], v[212:213]
	v_pk_mul_f32 v[28:29], v[28:29], v[248:249]
	v_pk_mul_f32 v[30:31], v[30:31], v[250:251]
	s_branch .Ldqc
